# overlap mode without the FFN-in->FFN-out grid barrier: per-WG pass-1 flags polled per 128-column block by FFN-out (same-XCD producers, census-guarded), deferred tiles unchanged
# speedup vs baseline: 1.0073x; 1.0073x over previous
_Z8mega_fwd4Args:
	s_add_u32 s12, s0, 0xe8
	v_and_b32_e32 v226, 0x3ff, v0
	s_addc_u32 s13, s1, 0
	v_cmp_gt_u32_e32 vcc, 64, v226
	s_and_saveexec_b64 s[4:5], vcc
	v_lshl_add_u32 v1, v226, 2, 0
	v_add_u32_e32 v1, 0x20000, v1
	v_mov_b32_e32 v2, 0
	ds_write_b32 v1, v2
	s_or_b64 exec, exec, s[4:5]
	s_load_dwordx2 s[66:67], s[0:1], 0xe8
	s_load_dword s68, s[0:1], 0xf0
	s_mov_b64 s[8:9], s[0:1]
	s_waitcnt lgkmcnt(0)
	s_barrier
	s_getreg_b32 s3, hwreg(HW_REG_XCC_ID, 0, 4)
	v_cmp_eq_u32_e64 s[78:79], 0, v226
	s_and_saveexec_b64 s[6:7], s[78:79]
	s_cbranch_execz .LBB0_5
	s_mov_b64 s[14:15], exec
	v_mbcnt_lo_u32_b32 v1, s14, 0
	v_mbcnt_hi_u32_b32 v1, s15, v1
	v_cmp_eq_u32_e32 vcc, 0, v1
	s_and_b64 s[4:5], exec, vcc
	s_mov_b64 exec, s[4:5]
	s_cbranch_execz .LBB0_5
	s_load_dwordx2 s[4:5], s[8:9], 0xe0
	s_and_b32 s10, s3, 15
	s_lshl_b32 s10, 1, s10
	s_and_b32 s11, s2, 7
	s_lshl_b32 s11, s11, 2
	s_add_i32 s11, s11, 0x9100
	s_lshl_b32 s3, s3, 8
	s_and_b32 s3, s3, 0xf00
	v_mov_b32_e32 v1, 0x4000
	s_waitcnt lgkmcnt(0)
	s_add_u32 s4, s4, s3
	s_addc_u32 s5, s5, 0
	s_bcnt1_i32_b64 s3, s[14:15]
	v_mov_b32_e32 v2, s3
	global_atomic_add v1, v2, s[4:5] offset:1024
	v_mov_b32_e32 v1, s11
	v_mov_b32_e32 v2, s10
	s_nop 1
	s_load_dwordx2 s[10:11], s[8:9], 0xe0
	s_waitcnt lgkmcnt(0)
	global_atomic_or v1, v2, s[10:11]

.LBB0_1297:
	s_nop 0
	v_readlane_b32 s4, v253, 62
	s_cmp_ge_i32 s4, 0x97a0
	s_cselect_b32 s100, 1, 0
	s_cbranch_scc0 .Lko_entry_done
	s_add_i32 s101, s101, 1
	s_load_dwordx2 s[8:9], s[0:1], 0xe0
	s_waitcnt lgkmcnt(0)
	s_load_dwordx8 s[24:31], s[8:9], 0x9100
	s_waitcnt lgkmcnt(0)
	s_mov_b32 s6, 0
	s_bcnt1_i32_b32 s4, s24
	s_add_i32 s6, s6, s4
	s_bcnt1_i32_b32 s4, s25
	s_add_i32 s6, s6, s4
	s_bcnt1_i32_b32 s4, s26
	s_add_i32 s6, s6, s4
	s_bcnt1_i32_b32 s4, s27
	s_add_i32 s6, s6, s4
	s_bcnt1_i32_b32 s4, s28
	s_add_i32 s6, s6, s4
	s_bcnt1_i32_b32 s4, s29
	s_add_i32 s6, s6, s4
	s_bcnt1_i32_b32 s4, s30
	s_add_i32 s6, s6, s4
	s_bcnt1_i32_b32 s4, s31
	s_add_i32 s6, s6, s4
	s_cmp_eq_u32 s6, 8
	s_cselect_b32 s100, 2, 1
	s_lshr_b32 s4, s2, 3
	s_mul_i32 s6, s4, 0xcccd
	s_lshr_b32 s6, s6, 18
	s_mul_i32 s8, s6, 5
	s_sub_i32 s4, s4, s8
	s_and_b32 s8, s2, 7
	s_mul_i32 s8, s8, 5
	s_add_i32 s4, s4, s8
	s_mov_b32 s8, 0
	s_nop 3
	v_writelane_b32 v253, s6, 36
	v_writelane_b32 v253, s4, 37
	v_writelane_b32 v253, s8, 38
	v_writelane_b32 v253, s6, 39
	v_writelane_b32 v253, s8, 40
	s_nop 1

.LBB0_1314:
	s_lshl_b32 s4, s68, 8
	v_add_u32_e32 v172, s4, v151
	s_addk_i32 s4, 0xe000
	s_lshr_b32 s4, s4, 10
	s_add_i32 s4, s4, 1
	s_cmp_gt_i32 s68, 31
	s_cselect_b32 s4, s4, 0
	s_mul_hi_u32 s44, s4, 0x5800
	s_mulk_i32 s4, 0x5800
	s_add_u32 s4, s55, s4
	s_addc_u32 s48, s56, s44
	s_lshl_b32 s44, s67, 8
	s_ashr_i32 s45, s44, 31
	s_lshl_b64 s[44:45], s[44:45], 2
	v_ashrrev_i32_e32 v173, 31, v172
	s_add_u32 s4, s4, s44
	v_lshl_add_u64 v[130:131], v[172:173], 2, s[28:29]
	s_addc_u32 s45, s48, s45
	global_load_dword v148, v[130:131], off
	global_load_dword v149, v[130:131], off offset:64
	global_load_dword v150, v[130:131], off offset:128
	global_load_dword v152, v[130:131], off offset:192
	global_load_dword v154, v[130:131], off offset:512
	global_load_dword v156, v[130:131], off offset:576
	global_load_dword v158, v[130:131], off offset:640
	global_load_dword v163, v[130:131], off offset:704
	s_add_u32 s44, s4, s63
	s_addc_u32 s45, s45, 0
	global_load_dwordx4 v[164:167], v159, s[44:45] offset:512
	global_load_dwordx4 v[134:137], v159, s[44:45]
	global_load_dwordx4 v[168:171], v159, s[44:45] offset:528
	global_load_dwordx4 v[130:133], v159, s[44:45] offset:16
	v_mov_b32_e32 v194, v122
	v_mov_b32_e32 v177, v118
	v_mov_b32_e32 v118, v127
	v_mov_b32_e32 v196, v124
	v_or_b32_e32 v199, 48, v172
	v_mov_b32_e32 v176, v126
	v_mov_b32_e32 v193, v120
	v_mov_b32_e32 v120, v129
	v_mov_b32_e32 v192, v128
	v_mov_b32_e32 v195, v114
	v_mov_b32_e32 v197, v116
	v_mov_b32_e32 v116, v125
	v_mov_b32_e32 v114, v123
	v_lshl_or_b32 v174, s67, 7, v155
	v_ashrrev_i32_e32 v175, 31, v174
	v_or_b32_e32 v173, 16, v172
	v_or_b32_e32 v179, 32, v172
	v_add_u32_e32 v162, 0x80, v172
	v_add_u32_e32 v161, 0x90, v172
	v_add_u32_e32 v160, 0xa0, v172
	v_add_u32_e32 v123, 0xb0, v172
	s_and_b64 vcc, exec, s[6:7]
	s_mov_b64 s[6:7], -1
	s_waitcnt vmcnt(0)
	v_fmamk_f32 v122, v148, 0x3a800000, v227
	v_rsq_f32_e32 v198, v122
	v_fmamk_f32 v124, v149, 0x3a800000, v227
	v_fmamk_f32 v126, v152, 0x3a800000, v227
	v_fmamk_f32 v127, v154, 0x3a800000, v227
	v_fmamk_f32 v125, v150, 0x3a800000, v227
	v_fmamk_f32 v129, v158, 0x3a800000, v227
	v_fmamk_f32 v148, v163, 0x3a800000, v227
	v_mov_b32_e32 v149, v134
	v_mov_b32_e32 v134, v165
	v_rsq_f32_e32 v122, v148
	v_mov_b32_e32 v148, v164
	v_pk_fma_f32 v[118:119], v[118:119], v[198:199], v[134:135] op_sel_hi:[1,0,1]
	v_pk_fma_f32 v[164:165], v[176:177], v[198:199], v[148:149] op_sel_hi:[1,0,1]
	v_mul_f32_e32 v176, 0xbfb8aa3b, v119
	v_exp_f32_e32 v176, v176
	v_mul_f32_e32 v163, 0xbfb8aa3b, v165
	v_exp_f32_e32 v163, v163
	v_fmamk_f32 v128, v156, 0x3a800000, v227
	v_add_f32_e32 v176, 1.0, v176
	v_rcp_f32_e32 v176, v176
	v_rsq_f32_e32 v156, v126
	v_rsq_f32_e32 v154, v127
	v_rsq_f32_e32 v150, v129
	v_mov_b32_e32 v129, v136
	v_mov_b32_e32 v136, v167
	v_mov_b32_e32 v126, v168
	v_mov_b32_e32 v127, v130
	v_rsq_f32_e32 v152, v128
	v_mov_b32_e32 v128, v166
	v_mov_b32_e32 v130, v169
	v_pk_fma_f32 v[120:121], v[120:121], v[198:199], v[136:137] op_sel_hi:[1,0,1]
	v_pk_fma_f32 v[168:169], v[194:195], v[198:199], v[126:127] op_sel_hi:[1,0,1]
	v_mul_f32_e32 v119, v119, v176
	v_pk_fma_f32 v[166:167], v[192:193], v[198:199], v[128:129] op_sel_hi:[1,0,1]
	v_mul_f32_e32 v192, 0xbfb8aa3b, v121
	v_mul_f32_e32 v118, v118, v119
	v_mul_f32_e32 v119, 0xbfb8aa3b, v169
	v_mul_f32_e32 v177, 0xbfb8aa3b, v167
	v_exp_f32_e32 v192, v192
	v_add_f32_e32 v163, 1.0, v163
	v_exp_f32_e32 v119, v119
	v_exp_f32_e32 v177, v177
	v_rcp_f32_e32 v163, v163
	v_pk_fma_f32 v[114:115], v[114:115], v[198:199], v[130:131] op_sel_hi:[1,0,1]
	v_add_f32_e32 v192, 1.0, v192
	v_add_f32_e32 v119, 1.0, v119
	v_add_f32_e32 v177, 1.0, v177
	v_rcp_f32_e32 v192, v192
	v_mul_f32_e32 v163, v165, v163
	v_rcp_f32_e32 v119, v119
	v_mul_f32_e32 v165, 0xbfb8aa3b, v115
	v_rcp_f32_e32 v177, v177
	v_exp_f32_e32 v165, v165
	v_rsq_f32_e32 v200, v124
	v_rsq_f32_e32 v158, v125
	v_mov_b32_e32 v124, v170
	v_mov_b32_e32 v125, v132
	v_mov_b32_e32 v132, v171
	v_pk_fma_f32 v[170:171], v[196:197], v[198:199], v[124:125] op_sel_hi:[1,0,1]
	v_mul_f32_e32 v121, v121, v192
	v_mul_f32_e32 v119, v169, v119
	v_pk_fma_f32 v[116:117], v[116:117], v[198:199], v[132:133] op_sel_hi:[1,0,1]
	v_mul_f32_e32 v163, v164, v163
	v_mul_f32_e32 v164, v167, v177
	v_mul_f32_e32 v120, v120, v121
	v_mul_f32_e32 v121, v168, v119
	v_add_f32_e32 v119, 1.0, v165
	v_mul_f32_e32 v165, 0xbfb8aa3b, v171
	v_mul_f32_e32 v164, v166, v164
	v_rcp_f32_e32 v119, v119
	v_exp_f32_e32 v165, v165
	v_mul_f32_e32 v166, 0xbfb8aa3b, v117
	v_exp_f32_e32 v166, v166
	v_mul_f32_e32 v115, v115, v119
	v_add_f32_e32 v119, 1.0, v165
	v_rcp_f32_e32 v119, v119
	v_add_f32_e32 v165, 1.0, v166
	v_rcp_f32_e32 v165, v165
	v_mul_f32_e32 v114, v114, v115
	v_mul_f32_e32 v115, v171, v119
	v_mul_f32_e32 v115, v170, v115
	v_mul_f32_e32 v117, v117, v165
	v_mul_f32_e32 v116, v116, v117
	v_cvt_pk_bf16_f32 v118, v163, v118
	v_cvt_pk_bf16_f32 v119, v164, v120
	v_cvt_pk_bf16_f32 v120, v121, v114
	v_cvt_pk_bf16_f32 v121, v115, v116
	v_mov_b64_e32 v[114:115], s[26:27]
	v_mad_i64_i32 v[164:165], s[44:45], v172, s33, v[114:115]
	v_lshlrev_b64 v[116:117], 1, v[174:175]
	v_lshl_add_u64 v[164:165], v[164:165], 0, v[116:117]
	global_store_dwordx4 v[164:165], v[118:121], off
	s_nop 1
	v_mov_b32_e32 v118, v110
	v_mov_b32_e32 v119, v106
	v_pk_fma_f32 v[118:119], v[118:119], v[200:201], v[148:149] op_sel_hi:[1,0,1]
	v_mov_b32_e32 v106, v111
	v_pk_fma_f32 v[106:107], v[106:107], v[200:201], v[134:135] op_sel_hi:[1,0,1]
	v_mov_b32_e32 v111, v108
	v_mov_b32_e32 v108, v113
	v_mov_b32_e32 v113, v98
	v_mov_b32_e32 v98, v103
	v_mov_b32_e32 v103, v100
	v_mul_f32_e32 v100, 0xbfb8aa3b, v119
	v_mov_b32_e32 v110, v112
	v_mov_b32_e32 v112, v102
	v_mov_b32_e32 v102, v104
	v_exp_f32_e32 v104, v100
	v_mul_f32_e32 v100, 0xbfb8aa3b, v107
	v_exp_f32_e32 v120, v100
	v_mov_b32_e32 v100, v105
	v_add_f32_e32 v104, 1.0, v104
	v_rcp_f32_e32 v104, v104
	v_add_f32_e32 v105, 1.0, v120
	v_rcp_f32_e32 v105, v105
	v_pk_fma_f32 v[110:111], v[110:111], v[200:201], v[128:129] op_sel_hi:[1,0,1]
	v_pk_fma_f32 v[108:109], v[108:109], v[200:201], v[136:137] op_sel_hi:[1,0,1]
	v_mul_f32_e32 v104, v119, v104
	v_mul_f32_e32 v105, v107, v105
	v_mul_f32_e32 v107, 0xbfb8aa3b, v111
	v_mul_f32_e32 v104, v118, v104
	v_exp_f32_e32 v107, v107
	v_mul_f32_e32 v118, 0xbfb8aa3b, v109
	v_exp_f32_e32 v118, v118
	v_pk_fma_f32 v[112:113], v[112:113], v[200:201], v[126:127] op_sel_hi:[1,0,1]
	v_mul_f32_e32 v105, v106, v105
	v_add_f32_e32 v106, 1.0, v107
	v_rcp_f32_e32 v106, v106
	v_add_f32_e32 v107, 1.0, v118
	v_mul_f32_e32 v118, 0xbfb8aa3b, v113
	v_rcp_f32_e32 v107, v107
	v_exp_f32_e32 v118, v118
	v_pk_fma_f32 v[98:99], v[98:99], v[200:201], v[130:131] op_sel_hi:[1,0,1]
	v_mul_f32_e32 v106, v111, v106
	v_mul_f32_e32 v106, v110, v106
	v_mul_f32_e32 v107, v109, v107
	v_add_f32_e32 v109, 1.0, v118
	v_mul_f32_e32 v110, 0xbfb8aa3b, v99
	v_rcp_f32_e32 v109, v109
	v_exp_f32_e32 v110, v110
	v_pk_fma_f32 v[102:103], v[102:103], v[200:201], v[124:125] op_sel_hi:[1,0,1]
	v_pk_fma_f32 v[100:101], v[100:101], v[200:201], v[132:133] op_sel_hi:[1,0,1]
	v_mul_f32_e32 v107, v108, v107
	v_mul_f32_e32 v108, v113, v109
	v_add_f32_e32 v109, 1.0, v110
	v_mul_f32_e32 v110, 0xbfb8aa3b, v103
	v_rcp_f32_e32 v109, v109
	v_exp_f32_e32 v110, v110
	v_mul_f32_e32 v111, 0xbfb8aa3b, v101
	v_exp_f32_e32 v111, v111
	v_mul_f32_e32 v99, v99, v109
	v_add_f32_e32 v109, 1.0, v110
	v_rcp_f32_e32 v109, v109
	v_add_f32_e32 v110, 1.0, v111
	v_rcp_f32_e32 v110, v110
	v_mul_f32_e32 v111, v98, v99
	v_mul_f32_e32 v98, v103, v109
	v_mul_f32_e32 v102, v102, v98
	v_mul_f32_e32 v98, v101, v110
	v_mul_f32_e32 v101, v100, v98
	v_mul_f32_e32 v108, v112, v108
	v_cvt_pk_bf16_f32 v98, v104, v105
	v_cvt_pk_bf16_f32 v99, v106, v107
	v_cvt_pk_bf16_f32 v100, v108, v111
	v_cvt_pk_bf16_f32 v101, v102, v101
	v_mad_i64_i32 v[102:103], s[44:45], v173, s33, v[114:115]
	v_lshl_add_u64 v[102:103], v[102:103], 0, v[116:117]
	global_store_dwordx4 v[102:103], v[98:101], off
	s_nop 1
	v_mov_b32_e32 v98, v94
	v_mov_b32_e32 v99, v90
	v_pk_fma_f32 v[98:99], v[98:99], v[158:159], v[148:149] op_sel_hi:[1,0,1]
	v_mov_b32_e32 v90, v95
	v_pk_fma_f32 v[90:91], v[90:91], v[158:159], v[134:135] op_sel_hi:[1,0,1]
	v_mov_b32_e32 v95, v92
	v_mov_b32_e32 v92, v97
	v_mov_b32_e32 v97, v82
	v_mov_b32_e32 v82, v87
	v_mov_b32_e32 v87, v84
	v_mul_f32_e32 v84, 0xbfb8aa3b, v99
	v_mov_b32_e32 v94, v96
	v_mov_b32_e32 v96, v86
	v_mov_b32_e32 v86, v88
	v_exp_f32_e32 v88, v84
	v_mul_f32_e32 v84, 0xbfb8aa3b, v91
	v_exp_f32_e32 v100, v84
	v_mov_b32_e32 v84, v89
	v_add_f32_e32 v88, 1.0, v88
	v_rcp_f32_e32 v88, v88
	v_add_f32_e32 v89, 1.0, v100
	v_rcp_f32_e32 v89, v89
	v_pk_fma_f32 v[94:95], v[94:95], v[158:159], v[128:129] op_sel_hi:[1,0,1]
	v_pk_fma_f32 v[92:93], v[92:93], v[158:159], v[136:137] op_sel_hi:[1,0,1]
	v_mul_f32_e32 v88, v99, v88
	v_mul_f32_e32 v89, v91, v89
	v_mul_f32_e32 v91, 0xbfb8aa3b, v95
	v_mul_f32_e32 v88, v98, v88
	v_exp_f32_e32 v91, v91
	v_mul_f32_e32 v98, 0xbfb8aa3b, v93
	v_exp_f32_e32 v98, v98
	v_pk_fma_f32 v[96:97], v[96:97], v[158:159], v[126:127] op_sel_hi:[1,0,1]
	v_mul_f32_e32 v89, v90, v89
	v_add_f32_e32 v90, 1.0, v91
	v_rcp_f32_e32 v90, v90
	v_add_f32_e32 v91, 1.0, v98
	v_mul_f32_e32 v98, 0xbfb8aa3b, v97
	v_rcp_f32_e32 v91, v91
	v_exp_f32_e32 v98, v98
	v_pk_fma_f32 v[82:83], v[82:83], v[158:159], v[130:131] op_sel_hi:[1,0,1]
	v_mul_f32_e32 v90, v95, v90
	v_mul_f32_e32 v90, v94, v90
	v_mul_f32_e32 v91, v93, v91
	v_add_f32_e32 v93, 1.0, v98
	v_mul_f32_e32 v94, 0xbfb8aa3b, v83
	v_rcp_f32_e32 v93, v93
	v_exp_f32_e32 v94, v94
	v_pk_fma_f32 v[86:87], v[86:87], v[158:159], v[124:125] op_sel_hi:[1,0,1]
	v_pk_fma_f32 v[84:85], v[84:85], v[158:159], v[132:133] op_sel_hi:[1,0,1]
	v_mul_f32_e32 v91, v92, v91
	v_mul_f32_e32 v92, v97, v93
	v_add_f32_e32 v93, 1.0, v94
	v_mul_f32_e32 v94, 0xbfb8aa3b, v87
	v_rcp_f32_e32 v93, v93
	v_exp_f32_e32 v94, v94
	v_mul_f32_e32 v95, 0xbfb8aa3b, v85
	v_exp_f32_e32 v95, v95
	v_mul_f32_e32 v83, v83, v93
	v_add_f32_e32 v93, 1.0, v94
	v_rcp_f32_e32 v93, v93
	v_add_f32_e32 v94, 1.0, v95
	v_rcp_f32_e32 v94, v94
	v_mul_f32_e32 v95, v82, v83
	v_mul_f32_e32 v82, v87, v93
	v_mul_f32_e32 v86, v86, v82
	v_mul_f32_e32 v82, v85, v94
	v_mul_f32_e32 v85, v84, v82
	v_mul_f32_e32 v92, v96, v92
	v_cvt_pk_bf16_f32 v82, v88, v89
	v_cvt_pk_bf16_f32 v83, v90, v91
	v_cvt_pk_bf16_f32 v84, v92, v95
	v_cvt_pk_bf16_f32 v85, v86, v85
	v_mad_i64_i32 v[86:87], s[44:45], v179, s33, v[114:115]
	v_lshl_add_u64 v[86:87], v[86:87], 0, v[116:117]
	global_store_dwordx4 v[86:87], v[82:85], off
	s_nop 1
	v_mov_b32_e32 v82, v78
	v_mov_b32_e32 v83, v74
	v_pk_fma_f32 v[82:83], v[82:83], v[156:157], v[148:149] op_sel_hi:[1,0,1]
	v_mov_b32_e32 v74, v79
	v_pk_fma_f32 v[74:75], v[74:75], v[156:157], v[134:135] op_sel_hi:[1,0,1]
	v_mov_b32_e32 v79, v76
	v_mov_b32_e32 v76, v81
	v_mov_b32_e32 v81, v66
	v_mov_b32_e32 v66, v71
	v_mov_b32_e32 v71, v68
	v_mul_f32_e32 v68, 0xbfb8aa3b, v83
	v_mov_b32_e32 v78, v80
	v_mov_b32_e32 v80, v70
	v_mov_b32_e32 v70, v72
	v_exp_f32_e32 v72, v68
	v_mul_f32_e32 v68, 0xbfb8aa3b, v75
	v_exp_f32_e32 v84, v68
	v_mov_b32_e32 v68, v73
	v_add_f32_e32 v72, 1.0, v72
	v_rcp_f32_e32 v72, v72
	v_add_f32_e32 v73, 1.0, v84
	v_rcp_f32_e32 v73, v73
	v_pk_fma_f32 v[78:79], v[78:79], v[156:157], v[128:129] op_sel_hi:[1,0,1]
	v_pk_fma_f32 v[76:77], v[76:77], v[156:157], v[136:137] op_sel_hi:[1,0,1]
	v_mul_f32_e32 v72, v83, v72
	v_mul_f32_e32 v73, v75, v73
	v_mul_f32_e32 v75, 0xbfb8aa3b, v79
	v_mul_f32_e32 v72, v82, v72
	v_exp_f32_e32 v75, v75
	v_mul_f32_e32 v82, 0xbfb8aa3b, v77
	v_exp_f32_e32 v82, v82
	v_pk_fma_f32 v[80:81], v[80:81], v[156:157], v[126:127] op_sel_hi:[1,0,1]
	v_mul_f32_e32 v73, v74, v73
	v_add_f32_e32 v74, 1.0, v75
	v_rcp_f32_e32 v74, v74
	v_add_f32_e32 v75, 1.0, v82
	v_mul_f32_e32 v82, 0xbfb8aa3b, v81
	v_rcp_f32_e32 v75, v75
	v_exp_f32_e32 v82, v82
	v_pk_fma_f32 v[66:67], v[66:67], v[156:157], v[130:131] op_sel_hi:[1,0,1]
	v_mul_f32_e32 v74, v79, v74
	v_mul_f32_e32 v74, v78, v74
	v_mul_f32_e32 v75, v77, v75
	v_add_f32_e32 v77, 1.0, v82
	v_mul_f32_e32 v78, 0xbfb8aa3b, v67
	v_rcp_f32_e32 v77, v77
	v_exp_f32_e32 v78, v78
	v_pk_fma_f32 v[70:71], v[70:71], v[156:157], v[124:125] op_sel_hi:[1,0,1]
	v_pk_fma_f32 v[68:69], v[68:69], v[156:157], v[132:133] op_sel_hi:[1,0,1]
	v_mul_f32_e32 v75, v76, v75
	v_mul_f32_e32 v76, v81, v77
	v_add_f32_e32 v77, 1.0, v78
	v_mul_f32_e32 v78, 0xbfb8aa3b, v71
	v_rcp_f32_e32 v77, v77
	v_exp_f32_e32 v78, v78
	v_mul_f32_e32 v79, 0xbfb8aa3b, v69
	v_exp_f32_e32 v79, v79
	v_mul_f32_e32 v67, v67, v77
	v_add_f32_e32 v77, 1.0, v78
	v_rcp_f32_e32 v77, v77
	v_add_f32_e32 v78, 1.0, v79
	v_rcp_f32_e32 v78, v78
	v_mul_f32_e32 v79, v66, v67
	v_mul_f32_e32 v66, v71, v77
	v_mul_f32_e32 v70, v70, v66
	v_mul_f32_e32 v66, v69, v78
	v_mul_f32_e32 v69, v68, v66
	v_mul_f32_e32 v76, v80, v76
	v_cvt_pk_bf16_f32 v66, v72, v73
	v_cvt_pk_bf16_f32 v67, v74, v75
	v_cvt_pk_bf16_f32 v68, v76, v79
	v_cvt_pk_bf16_f32 v69, v70, v69
	v_mad_i64_i32 v[70:71], s[44:45], v199, s33, v[114:115]
	v_lshl_add_u64 v[70:71], v[70:71], 0, v[116:117]
	global_store_dwordx4 v[70:71], v[66:69], off
	s_nop 1
	v_mov_b32_e32 v66, v62
	v_mov_b32_e32 v67, v58
	v_pk_fma_f32 v[66:67], v[66:67], v[154:155], v[148:149] op_sel_hi:[1,0,1]
	v_mov_b32_e32 v58, v63
	v_pk_fma_f32 v[58:59], v[58:59], v[154:155], v[134:135] op_sel_hi:[1,0,1]
	v_mov_b32_e32 v63, v60
	v_mov_b32_e32 v60, v65
	v_mov_b32_e32 v65, v50
	v_mov_b32_e32 v50, v55
	v_mov_b32_e32 v55, v52
	v_mul_f32_e32 v52, 0xbfb8aa3b, v67
	v_mov_b32_e32 v62, v64
	v_mov_b32_e32 v64, v54
	v_mov_b32_e32 v54, v56
	v_exp_f32_e32 v56, v52
	v_mul_f32_e32 v52, 0xbfb8aa3b, v59
	v_exp_f32_e32 v68, v52
	v_mov_b32_e32 v52, v57
	v_add_f32_e32 v56, 1.0, v56
	v_rcp_f32_e32 v56, v56
	v_add_f32_e32 v57, 1.0, v68
	v_rcp_f32_e32 v57, v57
	v_pk_fma_f32 v[62:63], v[62:63], v[154:155], v[128:129] op_sel_hi:[1,0,1]
	v_pk_fma_f32 v[60:61], v[60:61], v[154:155], v[136:137] op_sel_hi:[1,0,1]
	v_mul_f32_e32 v56, v67, v56
	v_mul_f32_e32 v57, v59, v57
	v_mul_f32_e32 v59, 0xbfb8aa3b, v63
	v_mul_f32_e32 v56, v66, v56
	v_exp_f32_e32 v59, v59
	v_mul_f32_e32 v66, 0xbfb8aa3b, v61
	v_exp_f32_e32 v66, v66
	v_pk_fma_f32 v[64:65], v[64:65], v[154:155], v[126:127] op_sel_hi:[1,0,1]
	v_mul_f32_e32 v57, v58, v57
	v_add_f32_e32 v58, 1.0, v59
	v_rcp_f32_e32 v58, v58
	v_add_f32_e32 v59, 1.0, v66
	v_mul_f32_e32 v66, 0xbfb8aa3b, v65
	v_rcp_f32_e32 v59, v59
	v_exp_f32_e32 v66, v66
	v_pk_fma_f32 v[50:51], v[50:51], v[154:155], v[130:131] op_sel_hi:[1,0,1]
	v_mul_f32_e32 v58, v63, v58
	v_mul_f32_e32 v58, v62, v58
	v_mul_f32_e32 v59, v61, v59
	v_add_f32_e32 v61, 1.0, v66
	v_mul_f32_e32 v62, 0xbfb8aa3b, v51
	v_rcp_f32_e32 v61, v61
	v_exp_f32_e32 v62, v62
	v_pk_fma_f32 v[54:55], v[54:55], v[154:155], v[124:125] op_sel_hi:[1,0,1]
	v_pk_fma_f32 v[52:53], v[52:53], v[154:155], v[132:133] op_sel_hi:[1,0,1]
	v_mul_f32_e32 v59, v60, v59
	v_mul_f32_e32 v60, v65, v61
	v_add_f32_e32 v61, 1.0, v62
	v_mul_f32_e32 v62, 0xbfb8aa3b, v55
	v_rcp_f32_e32 v61, v61
	v_exp_f32_e32 v62, v62
	v_mul_f32_e32 v63, 0xbfb8aa3b, v53
	v_exp_f32_e32 v63, v63
	v_mul_f32_e32 v51, v51, v61
	v_add_f32_e32 v61, 1.0, v62
	v_rcp_f32_e32 v61, v61
	v_add_f32_e32 v62, 1.0, v63
	v_rcp_f32_e32 v62, v62
	v_mul_f32_e32 v63, v50, v51
	v_mul_f32_e32 v50, v55, v61
	v_mul_f32_e32 v54, v54, v50
	v_mul_f32_e32 v50, v53, v62
	v_mul_f32_e32 v53, v52, v50
	v_mul_f32_e32 v60, v64, v60
	v_cvt_pk_bf16_f32 v50, v56, v57
	v_cvt_pk_bf16_f32 v51, v58, v59
	v_cvt_pk_bf16_f32 v52, v60, v63
	v_cvt_pk_bf16_f32 v53, v54, v53
	v_mad_i64_i32 v[54:55], s[44:45], v162, s33, v[114:115]
	v_lshl_add_u64 v[54:55], v[54:55], 0, v[116:117]
	global_store_dwordx4 v[54:55], v[50:53], off
	s_nop 1
	v_mov_b32_e32 v50, v46
	v_mov_b32_e32 v51, v42
	v_pk_fma_f32 v[50:51], v[50:51], v[152:153], v[148:149] op_sel_hi:[1,0,1]
	v_mov_b32_e32 v42, v47
	v_pk_fma_f32 v[42:43], v[42:43], v[152:153], v[134:135] op_sel_hi:[1,0,1]
	v_mov_b32_e32 v47, v44
	v_mov_b32_e32 v44, v49
	v_mov_b32_e32 v49, v34
	v_mov_b32_e32 v34, v39
	v_mov_b32_e32 v39, v36
	v_mul_f32_e32 v36, 0xbfb8aa3b, v51
	v_mov_b32_e32 v46, v48
	v_mov_b32_e32 v48, v38
	v_mov_b32_e32 v38, v40
	v_exp_f32_e32 v40, v36
	v_mul_f32_e32 v36, 0xbfb8aa3b, v43
	v_exp_f32_e32 v52, v36
	v_mov_b32_e32 v36, v41
	v_add_f32_e32 v40, 1.0, v40
	v_rcp_f32_e32 v40, v40
	v_add_f32_e32 v41, 1.0, v52
	v_rcp_f32_e32 v41, v41
	v_pk_fma_f32 v[46:47], v[46:47], v[152:153], v[128:129] op_sel_hi:[1,0,1]
	v_pk_fma_f32 v[44:45], v[44:45], v[152:153], v[136:137] op_sel_hi:[1,0,1]
	v_mul_f32_e32 v40, v51, v40
	v_mul_f32_e32 v41, v43, v41
	v_mul_f32_e32 v43, 0xbfb8aa3b, v47
	v_mul_f32_e32 v40, v50, v40
	v_exp_f32_e32 v43, v43
	v_mul_f32_e32 v50, 0xbfb8aa3b, v45
	v_exp_f32_e32 v50, v50
	v_pk_fma_f32 v[48:49], v[48:49], v[152:153], v[126:127] op_sel_hi:[1,0,1]
	v_mul_f32_e32 v41, v42, v41
	v_add_f32_e32 v42, 1.0, v43
	v_rcp_f32_e32 v42, v42
	v_add_f32_e32 v43, 1.0, v50
	v_mul_f32_e32 v50, 0xbfb8aa3b, v49
	v_rcp_f32_e32 v43, v43
	v_exp_f32_e32 v50, v50
	v_pk_fma_f32 v[34:35], v[34:35], v[152:153], v[130:131] op_sel_hi:[1,0,1]
	v_mul_f32_e32 v42, v47, v42
	v_mul_f32_e32 v42, v46, v42
	v_mul_f32_e32 v43, v45, v43
	v_add_f32_e32 v45, 1.0, v50
	v_mul_f32_e32 v46, 0xbfb8aa3b, v35
	v_rcp_f32_e32 v45, v45
	v_exp_f32_e32 v46, v46
	v_pk_fma_f32 v[38:39], v[38:39], v[152:153], v[124:125] op_sel_hi:[1,0,1]
	v_pk_fma_f32 v[36:37], v[36:37], v[152:153], v[132:133] op_sel_hi:[1,0,1]
	v_mul_f32_e32 v43, v44, v43
	v_mul_f32_e32 v44, v49, v45
	v_add_f32_e32 v45, 1.0, v46
	v_mul_f32_e32 v46, 0xbfb8aa3b, v39
	v_rcp_f32_e32 v45, v45
	v_exp_f32_e32 v46, v46
	v_mul_f32_e32 v47, 0xbfb8aa3b, v37
	v_exp_f32_e32 v47, v47
	v_mul_f32_e32 v35, v35, v45
	v_add_f32_e32 v45, 1.0, v46
	v_rcp_f32_e32 v45, v45
	v_add_f32_e32 v46, 1.0, v47
	v_rcp_f32_e32 v46, v46
	v_mul_f32_e32 v47, v34, v35
	v_mul_f32_e32 v34, v39, v45
	v_mul_f32_e32 v38, v38, v34
	v_mul_f32_e32 v34, v37, v46
	v_mul_f32_e32 v37, v36, v34
	v_mul_f32_e32 v44, v48, v44
	v_cvt_pk_bf16_f32 v34, v40, v41
	v_cvt_pk_bf16_f32 v35, v42, v43
	v_cvt_pk_bf16_f32 v36, v44, v47
	v_cvt_pk_bf16_f32 v37, v38, v37
	v_mad_i64_i32 v[38:39], s[44:45], v161, s33, v[114:115]
	v_lshl_add_u64 v[38:39], v[38:39], 0, v[116:117]
	global_store_dwordx4 v[38:39], v[34:37], off
	s_nop 1
	v_mov_b32_e32 v34, v30
	v_mov_b32_e32 v35, v26
	v_pk_fma_f32 v[34:35], v[34:35], v[150:151], v[148:149] op_sel_hi:[1,0,1]
	v_mov_b32_e32 v26, v31
	v_pk_fma_f32 v[26:27], v[26:27], v[150:151], v[134:135] op_sel_hi:[1,0,1]
	v_mov_b32_e32 v31, v28
	v_mov_b32_e32 v28, v33
	v_mov_b32_e32 v33, v18
	v_mov_b32_e32 v18, v23
	v_mov_b32_e32 v23, v20
	v_mul_f32_e32 v20, 0xbfb8aa3b, v35
	v_mov_b32_e32 v30, v32
	v_mov_b32_e32 v32, v22
	v_mov_b32_e32 v22, v24
	v_exp_f32_e32 v24, v20
	v_mul_f32_e32 v20, 0xbfb8aa3b, v27
	v_exp_f32_e32 v36, v20
	v_mov_b32_e32 v20, v25
	v_add_f32_e32 v24, 1.0, v24
	v_rcp_f32_e32 v24, v24
	v_add_f32_e32 v25, 1.0, v36
	v_rcp_f32_e32 v25, v25
	v_pk_fma_f32 v[30:31], v[30:31], v[150:151], v[128:129] op_sel_hi:[1,0,1]
	v_pk_fma_f32 v[28:29], v[28:29], v[150:151], v[136:137] op_sel_hi:[1,0,1]
	v_mul_f32_e32 v24, v35, v24
	v_mul_f32_e32 v25, v27, v25
	v_mul_f32_e32 v27, 0xbfb8aa3b, v31
	v_mul_f32_e32 v24, v34, v24
	v_exp_f32_e32 v27, v27
	v_mul_f32_e32 v34, 0xbfb8aa3b, v29
	v_exp_f32_e32 v34, v34
	v_pk_fma_f32 v[32:33], v[32:33], v[150:151], v[126:127] op_sel_hi:[1,0,1]
	v_mul_f32_e32 v25, v26, v25
	v_add_f32_e32 v26, 1.0, v27
	v_rcp_f32_e32 v26, v26
	v_add_f32_e32 v27, 1.0, v34
	v_mul_f32_e32 v34, 0xbfb8aa3b, v33
	v_rcp_f32_e32 v27, v27
	v_exp_f32_e32 v34, v34
	v_pk_fma_f32 v[18:19], v[18:19], v[150:151], v[130:131] op_sel_hi:[1,0,1]
	v_mul_f32_e32 v26, v31, v26
	v_mul_f32_e32 v26, v30, v26
	v_mul_f32_e32 v27, v29, v27
	v_add_f32_e32 v29, 1.0, v34
	v_mul_f32_e32 v30, 0xbfb8aa3b, v19
	v_rcp_f32_e32 v29, v29
	v_exp_f32_e32 v30, v30
	v_pk_fma_f32 v[22:23], v[22:23], v[150:151], v[124:125] op_sel_hi:[1,0,1]
	v_pk_fma_f32 v[20:21], v[20:21], v[150:151], v[132:133] op_sel_hi:[1,0,1]
	v_mul_f32_e32 v27, v28, v27
	v_mul_f32_e32 v28, v33, v29
	v_add_f32_e32 v29, 1.0, v30
	v_mul_f32_e32 v30, 0xbfb8aa3b, v23
	v_rcp_f32_e32 v29, v29
	v_exp_f32_e32 v30, v30
	v_mul_f32_e32 v31, 0xbfb8aa3b, v21
	v_exp_f32_e32 v31, v31
	v_mul_f32_e32 v19, v19, v29
	v_add_f32_e32 v29, 1.0, v30
	v_rcp_f32_e32 v29, v29
	v_add_f32_e32 v30, 1.0, v31
	v_rcp_f32_e32 v30, v30
	v_mul_f32_e32 v31, v18, v19
	v_mul_f32_e32 v18, v23, v29
	v_mul_f32_e32 v22, v22, v18
	v_mul_f32_e32 v18, v21, v30
	v_mul_f32_e32 v21, v20, v18
	v_mul_f32_e32 v28, v32, v28
	v_cvt_pk_bf16_f32 v18, v24, v25
	v_cvt_pk_bf16_f32 v19, v26, v27
	v_cvt_pk_bf16_f32 v20, v28, v31
	v_cvt_pk_bf16_f32 v21, v22, v21
	v_mad_i64_i32 v[22:23], s[44:45], v160, s33, v[114:115]
	v_lshl_add_u64 v[22:23], v[22:23], 0, v[116:117]
	global_store_dwordx4 v[22:23], v[18:21], off
	s_nop 1
	v_mov_b32_e32 v18, v14
	v_mov_b32_e32 v19, v10
	v_pk_fma_f32 v[18:19], v[18:19], v[122:123], v[148:149] op_sel_hi:[1,0,1]
	v_mov_b32_e32 v10, v15
	v_mov_b32_e32 v15, v12
	v_mov_b32_e32 v12, v17
	v_mov_b32_e32 v17, v6
	v_mov_b32_e32 v6, v3
	v_pk_fma_f32 v[10:11], v[10:11], v[122:123], v[134:135] op_sel_hi:[1,0,1]
	v_mov_b32_e32 v14, v16
	v_mov_b32_e32 v16, v2
	v_pk_fma_f32 v[2:3], v[6:7], v[122:123], v[130:131] op_sel_hi:[1,0,1]
	v_mov_b32_e32 v6, v4
	v_mul_f32_e32 v4, 0xbfb8aa3b, v19
	v_mov_b32_e32 v7, v8
	v_exp_f32_e32 v4, v4
	v_mul_f32_e32 v8, 0xbfb8aa3b, v11
	v_exp_f32_e32 v20, v8
	v_pk_fma_f32 v[14:15], v[14:15], v[122:123], v[128:129] op_sel_hi:[1,0,1]
	v_add_f32_e32 v4, 1.0, v4
	v_rcp_f32_e32 v21, v4
	v_add_f32_e32 v4, 1.0, v20
	v_rcp_f32_e32 v20, v4
	v_mov_b32_e32 v8, v5
	v_pk_fma_f32 v[12:13], v[12:13], v[122:123], v[136:137] op_sel_hi:[1,0,1]
	v_pk_fma_f32 v[4:5], v[8:9], v[122:123], v[132:133] op_sel_hi:[1,0,1]
	v_mul_f32_e32 v8, v19, v21
	v_mul_f32_e32 v9, v11, v20
	v_mul_f32_e32 v11, 0xbfb8aa3b, v15
	v_mul_f32_e32 v8, v18, v8
	v_exp_f32_e32 v11, v11
	v_mul_f32_e32 v18, 0xbfb8aa3b, v13
	v_exp_f32_e32 v18, v18
	v_pk_fma_f32 v[16:17], v[16:17], v[122:123], v[126:127] op_sel_hi:[1,0,1]
	v_mul_f32_e32 v9, v10, v9
	v_add_f32_e32 v10, 1.0, v11
	v_rcp_f32_e32 v10, v10
	v_add_f32_e32 v11, 1.0, v18
	v_mul_f32_e32 v18, 0xbfb8aa3b, v17
	v_rcp_f32_e32 v11, v11
	v_exp_f32_e32 v18, v18
	v_mul_f32_e32 v10, v15, v10
	v_mul_f32_e32 v10, v14, v10
	v_mul_f32_e32 v11, v13, v11
	v_add_f32_e32 v13, 1.0, v18
	v_mul_f32_e32 v14, 0xbfb8aa3b, v3
	v_rcp_f32_e32 v13, v13
	v_exp_f32_e32 v14, v14
	v_pk_fma_f32 v[6:7], v[6:7], v[122:123], v[124:125] op_sel_hi:[1,0,1]
	v_mul_f32_e32 v11, v12, v11
	v_mul_f32_e32 v12, v17, v13
	v_add_f32_e32 v13, 1.0, v14
	v_mul_f32_e32 v14, 0xbfb8aa3b, v7
	v_rcp_f32_e32 v13, v13
	v_exp_f32_e32 v14, v14
	v_mul_f32_e32 v15, 0xbfb8aa3b, v5
	v_exp_f32_e32 v15, v15
	v_mul_f32_e32 v3, v3, v13
	v_add_f32_e32 v13, 1.0, v14
	v_rcp_f32_e32 v13, v13
	v_add_f32_e32 v14, 1.0, v15
	v_rcp_f32_e32 v14, v14
	v_mul_f32_e32 v15, v2, v3
	v_mul_f32_e32 v2, v7, v13
	v_mul_f32_e32 v6, v6, v2
	v_mul_f32_e32 v2, v5, v14
	v_mul_f32_e32 v5, v4, v2
	v_mul_f32_e32 v12, v16, v12
	v_cvt_pk_bf16_f32 v2, v8, v9
	v_cvt_pk_bf16_f32 v3, v10, v11
	v_cvt_pk_bf16_f32 v4, v12, v15
	v_cvt_pk_bf16_f32 v5, v6, v5
	v_mad_i64_i32 v[6:7], s[44:45], v123, s33, v[114:115]
	v_lshl_add_u64 v[6:7], v[6:7], 0, v[116:117]
	global_store_dwordx4 v[6:7], v[2:5], off
	s_cmp_lg_u32 s100, 2
	s_cbranch_scc1 .Lko_p1_no
	s_cmp_lg_u32 s62, 3
	s_cbranch_scc1 .Lko_p1_no
	s_waitcnt vmcnt(0)
	s_barrier
	s_and_saveexec_b64 s[44:45], s[78:79]
	s_cbranch_execz .Lko_p1_done
	s_load_dwordx2 s[48:49], s[0:1], 0xe0
	s_lshl_b32 s4, s101, 8
	s_add_i32 s4, s4, s2
	s_lshl_b32 s4, s4, 2
	s_add_i32 s4, s4, 0xb000
	v_mov_b32_e32 v192, 0
	s_waitcnt lgkmcnt(0)
	s_add_u32 s48, s48, s4
	s_addc_u32 s49, s49, 0
	s_nop 4
	global_atomic_add v192, v252, s[48:49]

.Lko_p1_no:
	s_cmp_lg_u32 s100, 1
	s_cbranch_scc1 .Lko_nog
	s_cmp_lg_u32 s62, 3
	s_cbranch_scc1 .Lko_nog
	s_cmp_lt_u32 s2, 0xa0
	s_cbranch_scc1 .Lko_nog
	s_mov_b32 s4, 0
	s_nop 2
	v_writelane_b32 v255, s4, 61
	v_writelane_b32 v255, s8, 1
	v_writelane_b32 v255, s9, 2
	v_writelane_b32 v255, s10, 3
	v_writelane_b32 v255, s11, 4
	v_writelane_b32 v255, s12, 5
	v_writelane_b32 v255, s13, 6
	v_writelane_b32 v255, s22, 7
	v_writelane_b32 v255, s24, 8
	v_writelane_b32 v255, s25, 9
	v_writelane_b32 v255, s26, 10
	v_writelane_b32 v255, s27, 11
	v_writelane_b32 v255, s28, 12
	v_writelane_b32 v255, s29, 13
	v_writelane_b32 v255, s30, 14
	v_writelane_b32 v255, s31, 15
	v_writelane_b32 v255, s36, 16
	v_writelane_b32 v255, s37, 17
	v_writelane_b32 v255, s38, 18
	v_writelane_b32 v255, s39, 19
	v_writelane_b32 v255, s40, 20
	v_writelane_b32 v255, s41, 21
	v_writelane_b32 v255, s42, 22
	v_writelane_b32 v255, s43, 23
	v_writelane_b32 v255, s52, 24
	v_writelane_b32 v255, s53, 25
	v_writelane_b32 v255, s70, 26
	v_writelane_b32 v255, s71, 27
	v_writelane_b32 v255, s74, 28
	v_writelane_b32 v255, s75, 29
	v_writelane_b32 v255, s76, 30
	v_writelane_b32 v255, s77, 31
	v_writelane_b32 v255, s78, 32
	v_writelane_b32 v255, s79, 33
	v_writelane_b32 v255, s82, 34
	v_writelane_b32 v255, s83, 35
	v_writelane_b32 v255, s84, 36
	v_writelane_b32 v255, s85, 37
	v_writelane_b32 v255, s90, 38
	v_writelane_b32 v255, s91, 39
	v_writelane_b32 v255, s92, 40
	v_writelane_b32 v255, s93, 41
	v_writelane_b32 v255, s94, 42
	v_writelane_b32 v255, s95, 43
	v_writelane_b32 v255, s96, 44
	v_writelane_b32 v255, s97, 45
	v_writelane_b32 v255, vcc_lo, 46
	v_writelane_b32 v255, vcc_hi, 47
	v_mov_b32_e32 v200, v0
	v_mov_b32_e32 v201, v2
	v_mov_b32_e32 v202, v3
	v_mov_b32_e32 v203, v4
	v_mov_b32_e32 v204, v5
	v_mov_b32_e32 v205, v6
	v_mov_b32_e32 v206, v7
	v_mov_b32_e32 v207, v8
	v_mov_b32_e32 v208, v9
	v_mov_b32_e32 v209, v10
	v_mov_b32_e32 v210, v11
	v_mov_b32_e32 v211, v12
	v_mov_b32_e32 v212, v13
	v_mov_b32_e32 v213, v14
	v_mov_b32_e32 v214, v15
	v_mov_b32_e32 v215, v16
	v_mov_b32_e32 v216, v17
	s_mov_b64 s[10:11], s[0:1]
	s_getreg_b32 s4, hwreg(HW_REG_XCC_ID, 0, 4)
	s_waitcnt vmcnt(0)
	s_waitcnt lgkmcnt(0)
	s_barrier
	s_and_saveexec_b64 s[8:9], s[78:79]
	s_cbranch_execz .Lko_g1440
	v_readlane_b32 s12, v253, 60
	s_load_dwordx2 s[10:11], s[10:11], 0xe0
	s_waitcnt vmcnt(0) expcnt(0) lgkmcnt(0)
	v_mov_b32_e32 v0, s12
	ds_read_b32 v3, v0
	v_readlane_b32 s12, v253, 61
	s_and_b32 s4, s4, 15
	s_waitcnt lgkmcnt(0)
	v_cmp_ne_u32_e32 vcc, 0, v3
	v_mov_b32_e32 v0, s12
	ds_read_b32 v2, v0
	s_cbranch_vccnz .Lko_g1404
	s_add_u32 s12, s10, 0x4200
	s_addc_u32 s13, s11, 0
	s_add_u32 s24, s10, 0x4400
	s_addc_u32 s25, s11, 0
	s_add_u32 s26, s10, 0x4500
	s_addc_u32 s27, s11, 0
	s_add_u32 s28, s10, 0x4600
	s_addc_u32 s29, s11, 0
	s_add_u32 s36, s10, 0x4700
	s_addc_u32 s37, s11, 0
	s_add_u32 s40, s10, 0x4800
	s_addc_u32 s41, s11, 0
	s_add_u32 s42, s10, 0x4900
	s_addc_u32 s43, s11, 0
	s_add_u32 s44, s10, 0x4a00
	s_addc_u32 s45, s11, 0
	s_add_u32 s48, s10, 0x4b00
	s_addc_u32 s49, s11, 0
	s_add_u32 s52, s10, 0x4c00
	s_addc_u32 s53, s11, 0
	s_add_u32 s70, s10, 0x4d00
	s_addc_u32 s71, s11, 0
	s_add_u32 s74, s10, 0x4e00
	s_addc_u32 s75, s11, 0
	s_add_u32 s76, s10, 0x4f00
	s_addc_u32 s77, s11, 0
	s_add_u32 s78, s10, 0x5000
	s_addc_u32 s79, s11, 0
	s_add_u32 s82, s10, 0x5100
	s_addc_u32 s83, s11, 0
	s_add_u32 s90, s10, 0x5200
	s_addc_u32 s91, s11, 0
	s_add_u32 s92, s10, 0x5300
	s_addc_u32 s93, s11, 0
	s_mov_b32 s22, 1
	s_branch .Lko_g1392

.LBB0_1387:
	s_mov_b64 s[10:11], s[0:1]
	s_getreg_b32 s4, hwreg(HW_REG_XCC_ID, 0, 4)
	s_cmp_eq_u32 s100, 2
	s_cbranch_scc1 .Lko_fast_g1
	s_cmp_eq_u32 s100, 0
	s_cbranch_scc1 .Lko_g1_do
	s_cmp_lt_u32 s2, 0xa0
	s_cbranch_scc0 .Lko_w_entry

.Lko_fast_g1:
	s_cmp_lt_u32 s2, 0xa0
	s_cbranch_scc0 .Lko_g1_skip
	v_readlane_b32 s22, v253, 45
	s_load_dwordx2 s[12:13], s[0:1], 0xe0
	s_mul_i32 s24, s22, 0xcccd
	s_lshr_b32 s24, s24, 18
	s_mul_i32 s25, s24, 5
	s_sub_i32 s25, s22, s25
	s_lshl_b32 s26, s25, 3
	s_or_b32 s26, s26, s24
	s_add_i32 s25, s25, 5
	s_lshl_b32 s27, s25, 3
	s_or_b32 s27, s27, s24
	s_lshl_b32 s22, s101, 8
	s_add_i32 s26, s26, s22
	s_add_i32 s27, s27, s22
	s_lshl_b32 s26, s26, 2
	s_lshl_b32 s27, s27, 2
	s_add_i32 s26, s26, 0xb000
	s_add_i32 s27, s27, 0xb000
	v_mov_b32_e32 v2, s26
	v_mov_b32_e32 v3, s27
	s_mov_b32 s22, 0
	s_waitcnt lgkmcnt(0)
.Lko_fg_spin:
	global_load_dword v4, v2, s[12:13] sc1
	global_load_dword v5, v3, s[12:13] sc1
	s_waitcnt vmcnt(0)
	v_min_u32_e32 v4, v4, v5
	s_nop 0
	v_readfirstlane_b32 s24, v4
	s_cmp_lg_u32 s24, 0
	s_cbranch_scc1 .Lko_g1_skip
	s_sleep 2
	s_add_i32 s22, s22, 1
	s_cmp_lt_u32 s22, 0x8000
	s_cbranch_scc1 .Lko_fg_spin
	s_branch .Lko_g1_skip

.LBB0_1474:
	s_cmp_eq_u32 s100, 2
	s_cbranch_scc0 .Lko_oldp
	s_lshr_b32 s89, s82, 1
	s_add_i32 s89, s89, 1
	s_cmp_gt_u32 s89, 21
	s_cbranch_scc1 .Lko_nopoll
	s_load_dwordx2 s[90:91], s[0:1], 0xe0
	s_cmp_eq_u32 s82, 0
	s_cbranch_scc1 .Lko_fissue
	v_readfirstlane_b32 s83, v248
	s_cmp_lg_u32 s83, 0
	s_cbranch_scc1 .Lko_fissue

	s_cmp_lt_u32 s89, 19
	s_cbranch_scc1 .Lko_a1_c
	s_cmp_lg_u32 s89, 19
	s_cbranch_scc1 .Lko_ad_c
	s_cmp_lt_u32 s84, 8
	s_cbranch_scc0 .Lko_ad_c
	s_add_i32 s4, s84, 0xf8
	s_branch .Lko_ap_c
.Lko_ad_c:
	s_lshl_b32 s4, s101, 6
	s_add_i32 s4, s4, s84
	s_lshl_b32 s4, s4, 2
	s_add_i32 s4, s4, s89
	s_sub_i32 s4, s4, 19
	s_lshl_b32 s4, s4, 2
	s_add_i32 s4, s4, 0x8000
	s_branch .Lko_ae_c
.Lko_a1_c:
	s_mul_i32 s83, s84, 0xcccd
	s_lshr_b32 s83, s83, 18
	s_mul_i32 s92, s83, 5
	s_sub_i32 s92, s84, s92
	s_mul_i32 s4, s89, 5
	s_add_i32 s92, s92, s4
	s_and_b32 s92, s92, 31
	s_lshl_b32 s92, s92, 3
	s_or_b32 s4, s92, s83
.Lko_ap_c:
	s_lshl_b32 s83, s101, 8
	s_add_i32 s4, s4, s83
	s_lshl_b32 s4, s4, 2
	s_add_i32 s4, s4, 0xb000
.Lko_ae_c:
	v_mov_b32_e32 v251, s4
	s_mov_b32 s92, 0
	s_waitcnt lgkmcnt(0)
.Lko_fspin:
	global_load_dword v248, v251, s[90:91] sc1
	s_waitcnt vmcnt(0)
	v_readfirstlane_b32 s83, v248
	s_cmp_lg_u32 s83, 0
	s_cbranch_scc1 .Lko_fissue
	s_sleep 4
	s_add_i32 s92, s92, 1
	s_cmp_lt_u32 s92, 0x4000
	s_cbranch_scc1 .Lko_fspin
.Lko_fissue:
	s_waitcnt lgkmcnt(0)
	s_add_i32 s89, s89, 1
	s_cmp_gt_u32 s89, 21
	s_cbranch_scc1 .Lko_nopoll

	s_cmp_lt_u32 s89, 19
	s_cbranch_scc1 .Lko_a1_p
	s_cmp_lg_u32 s89, 19
	s_cbranch_scc1 .Lko_ad_p
	s_cmp_lt_u32 s84, 8
	s_cbranch_scc0 .Lko_ad_p
	s_add_i32 s4, s84, 0xf8
	s_branch .Lko_ap_p

.Lko_ae_p:
	v_mov_b32_e32 v251, s4
	s_waitcnt lgkmcnt(0)
	s_nop 0
	global_load_dword v248, v251, s[90:91] sc1
	s_branch .Lko_nopoll
